# attention first-query-block path: the 36 masked bias lookups issued together (one LDS wait), v_cndmask instead of 36 exec-masked round trips
# baseline (speedup 1.0000x reference)
.LBB0_352:
	s_cbranch_execz .LBB0_426
	ds_read_b32 v68, v187 offset:512
	ds_read_b32 v69, v191 offset:512
	ds_read_b32 v70, v192 offset:512
	ds_read_b32 v71, v193 offset:512
	ds_read_b32 v142, v194 offset:512
	ds_read_b32 v143, v195 offset:512
	ds_read_b32 v140, v196 offset:512
	ds_read_b32 v141, v197 offset:512
	ds_read_b32 v144, v198 offset:512
	ds_read_b32 v145, v200 offset:512
	ds_read_b32 v146, v201 offset:512
	ds_read_b32 v147, v202 offset:512
	ds_read_b32 v148, v203 offset:512
	ds_read_b32 v149, v210 offset:512
	ds_read_b32 v150, v211 offset:512
	ds_read_b32 v151, v212 offset:512
	ds_read_b32 v152, v213 offset:512
	ds_read_b32 v153, v214 offset:512
	ds_read_b32 v154, v215 offset:512
	ds_read_b32 v155, v216 offset:512
	ds_read_b32 v156, v217 offset:512
	ds_read_b32 v157, v218 offset:512
	ds_read_b32 v158, v219 offset:512
	ds_read_b32 v159, v220 offset:512
	ds_read_b32 v160, v221 offset:512
	ds_read_b32 v161, v222 offset:512
	ds_read_b32 v166, v223 offset:512
	ds_read_b32 v167, v224 offset:512
	ds_read_b32 v168, v225 offset:512
	ds_read_b32 v169, v226 offset:512
	ds_read_b32 v170, v227 offset:512
	ds_read_b32 v171, v228 offset:512
	ds_read_b32 v88, v229 offset:512
	ds_read_b32 v89, v230 offset:512
	ds_read_b32 v90, v231 offset:512
	ds_read_b32 v91, v232 offset:512
	v_mov_b32_e32 v0, 0xff800000
	s_waitcnt lgkmcnt(0)
	v_readlane_b32 s34, v254, 39
	v_readlane_b32 s35, v254, 40
	v_add_f32_e32 v68, v108, v68
	s_nop 1
	v_cndmask_b32_e64 v68, v0, v68, s[34:35]
	v_readlane_b32 s34, v254, 41
	v_readlane_b32 s35, v254, 42
	v_add_f32_e32 v69, v109, v69
	s_nop 1
	v_cndmask_b32_e64 v69, v0, v69, s[34:35]
	v_readlane_b32 s34, v254, 35
	v_readlane_b32 s35, v254, 36
	v_add_f32_e32 v70, v110, v70
	s_nop 1
	v_cndmask_b32_e64 v70, v0, v70, s[34:35]
	v_readlane_b32 s34, v254, 25
	v_readlane_b32 s35, v254, 26
	v_add_f32_e32 v71, v111, v71
	s_nop 1
	v_cndmask_b32_e64 v71, v0, v71, s[34:35]
	v_readlane_b32 s34, v254, 33
	v_readlane_b32 s35, v254, 34
	v_add_f32_e32 v142, v104, v142
	s_nop 1
	v_cndmask_b32_e64 v142, v0, v142, s[34:35]
	v_readlane_b32 s34, v254, 27
	v_readlane_b32 s35, v254, 28
	v_add_f32_e32 v143, v105, v143
	s_nop 1
	v_cndmask_b32_e64 v143, v0, v143, s[34:35]
	v_readlane_b32 s34, v254, 43
	v_readlane_b32 s35, v254, 44
	v_add_f32_e32 v140, v106, v140
	s_nop 1
	v_cndmask_b32_e64 v140, v0, v140, s[34:35]
	v_readlane_b32 s34, v254, 37
	v_readlane_b32 s35, v254, 38
	v_add_f32_e32 v141, v107, v141
	s_nop 1
	v_cndmask_b32_e64 v141, v0, v141, s[34:35]
	v_readlane_b32 s34, v254, 29
	v_readlane_b32 s35, v254, 30
	v_add_f32_e32 v144, v100, v144
	s_nop 1
	v_cndmask_b32_e64 v144, v0, v144, s[34:35]
	v_readlane_b32 s34, v254, 31
	v_readlane_b32 s35, v254, 32
	v_add_f32_e32 v145, v101, v145
	s_nop 1
	v_cndmask_b32_e64 v145, v0, v145, s[34:35]
	v_readlane_b32 s34, v254, 45
	v_readlane_b32 s35, v254, 46
	v_add_f32_e32 v146, v102, v146
	s_nop 1
	v_cndmask_b32_e64 v146, v0, v146, s[34:35]
	v_readlane_b32 s34, v254, 47
	v_readlane_b32 s35, v254, 48
	v_add_f32_e32 v147, v103, v147
	s_nop 1
	v_cndmask_b32_e64 v147, v0, v147, s[34:35]
	v_readlane_b32 s34, v254, 49
	v_readlane_b32 s35, v254, 50
	v_add_f32_e32 v148, v96, v148
	s_nop 1
	v_cndmask_b32_e64 v148, v0, v148, s[34:35]
	v_readlane_b32 s34, v254, 51
	v_readlane_b32 s35, v254, 52
	v_add_f32_e32 v149, v97, v149
	s_nop 1
	v_cndmask_b32_e64 v149, v0, v149, s[34:35]
	v_readlane_b32 s34, v254, 53
	v_readlane_b32 s35, v254, 54
	v_add_f32_e32 v150, v98, v150
	s_nop 1
	v_cndmask_b32_e64 v150, v0, v150, s[34:35]
	v_readlane_b32 s34, v254, 55
	v_readlane_b32 s35, v254, 56
	v_add_f32_e32 v151, v99, v151
	s_nop 1
	v_cndmask_b32_e64 v151, v0, v151, s[34:35]
	v_readlane_b32 s34, v254, 57
	v_readlane_b32 s35, v254, 58
	v_add_f32_e32 v152, v92, v152
	s_nop 1
	v_cndmask_b32_e64 v152, v0, v152, s[34:35]
	v_readlane_b32 s34, v254, 59
	v_readlane_b32 s35, v254, 60
	v_add_f32_e32 v153, v93, v153
	s_nop 1
	v_cndmask_b32_e64 v153, v0, v153, s[34:35]
	v_readlane_b32 s34, v254, 61
	v_readlane_b32 s35, v254, 62
	v_add_f32_e32 v154, v94, v154
	s_nop 1
	v_cndmask_b32_e64 v154, v0, v154, s[34:35]
	v_readlane_b32 s34, v254, 63
	v_readlane_b32 s35, v255, 0
	v_add_f32_e32 v155, v95, v155
	s_nop 1
	v_cndmask_b32_e64 v155, v0, v155, s[34:35]
	v_readlane_b32 s34, v255, 1
	v_readlane_b32 s35, v255, 2
	v_add_f32_e32 v156, v84, v156
	s_nop 1
	v_cndmask_b32_e64 v156, v0, v156, s[34:35]
	v_add_f32_e32 v157, v85, v157
	v_cndmask_b32_e64 v157, v0, v157, s[60:61]
	v_add_f32_e32 v158, v86, v158
	v_cndmask_b32_e64 v158, v0, v158, s[62:63]
	v_add_f32_e32 v159, v87, v159
	v_cndmask_b32_e64 v159, v0, v159, s[64:65]
	v_add_f32_e32 v160, v80, v160
	v_cndmask_b32_e64 v160, v0, v160, s[66:67]
	v_add_f32_e32 v161, v81, v161
	v_cndmask_b32_e64 v161, v0, v161, s[68:69]
	v_add_f32_e32 v166, v82, v166
	v_cndmask_b32_e64 v166, v0, v166, s[70:71]
	v_add_f32_e32 v167, v83, v167
	v_cndmask_b32_e64 v167, v0, v167, s[72:73]
	v_add_f32_e32 v168, v76, v168
	v_cndmask_b32_e64 v168, v0, v168, s[74:75]
	v_add_f32_e32 v169, v77, v169
	v_cndmask_b32_e64 v169, v0, v169, s[76:77]
	v_add_f32_e32 v170, v78, v170
	v_cndmask_b32_e64 v170, v0, v170, s[78:79]
	v_add_f32_e32 v171, v79, v171
	v_cndmask_b32_e64 v171, v0, v171, s[80:81]
	v_add_f32_e32 v88, v72, v88
	v_cndmask_b32_e64 v88, v0, v88, s[40:41]
	v_add_f32_e32 v89, v73, v89
	v_cndmask_b32_e64 v89, v0, v89, s[42:43]
	v_add_f32_e32 v90, v74, v90
	v_cndmask_b32_e64 v90, v0, v90, s[88:89]
	v_add_f32_e32 v91, v75, v91
	v_cndmask_b32_e64 v91, v0, v91, s[92:93]
	s_mov_b32 s24, 0xff800000
	v_max3_f32 v0, v68, s24, v69
	v_max3_f32 v0, v0, v70, v71
	v_max3_f32 v0, v0, v142, v143
	v_max3_f32 v0, v0, v140, v141
	v_max3_f32 v0, v0, v144, v145
	v_max3_f32 v0, v0, v146, v147
	v_max3_f32 v0, v0, v148, v149
	v_max3_f32 v0, v0, v150, v151
	v_max3_f32 v0, v0, v152, v153
	v_max3_f32 v0, v0, v154, v155
	v_max3_f32 v0, v0, v156, v157
	v_max3_f32 v0, v0, v158, v159
	v_max3_f32 v0, v0, v160, v161
	v_max3_f32 v0, v0, v166, v167
	v_max3_f32 v0, v0, v168, v169
	v_max3_f32 v0, v0, v170, v171
	v_max3_f32 v0, v0, v88, v89
	v_max3_f32 v0, v0, v90, v91
